# P3 fused epilogue: warm the residual x tile (one dword per line) before the first panel meeting
# baseline (speedup 1.0000x reference)
; __device__ __forceinline__ float ld_sc1(const float* p) { return __hip_atomic_load(p, __ATOMIC_RELAXED, __HIP_MEMORY_SCOPE_AGENT); }
; __device__ __forceinline__ float quad_row_sum(float s) { s += __shfl_xor(s, 16); s += __shfl_xor(s, 32); return s; }
; __device__ __forceinline__ float dot4(f32x4 v) { return (v[0] * v[0] + v[1] * v[1]) + (v[2] * v[2] + v[3] * v[3]); }
;     __device__ __forceinline__ void operator()(f32x4 (&acc)[2][2][4][2], const Unit& u, int wr, int wc, int fr, int fq) const {
;     ...
;             for (int m = 0; m < 4; ++m) { float s = 0.f;
; #pragma unroll
;                 for (int bj = 0; bj < 2; ++bj) s += dot4(acc[ai][bj][m][0]) + dot4(acc[ai][bj][m][1]);
;                 s = quad_row_sum(s);
;                 if (fq == 0) __hip_atomic_fetch_add(ss1 + row0 + ai * HALF + m * 16, s, __ATOMIC_RELAXED, __HIP_MEMORY_SCOPE_AGENT); }
;     ...
;             for (int m = 0; m < 4; ++m) { const int row = row0 + ai * HALF + m * 16;
;                 const float r1 = 1.f / sqrtf(ld_sc1(ss1 + row) * (1.f / 2048.f) + 1e-6f);
;                 const float* xrow = (row < 32768 ? xp + (size_t)row * 2048 : xs + (size_t)(row - 32768) * 2048) + col0;
;                 float s = 0.f;
; #pragma unroll
;                 for (int bj = 0; bj < 2; ++bj) { const f32x4 x0 = *(const f32x4*)(xrow + bj * HALF), x1 = *(const f32x4*)(xrow + bj * HALF + 4);
.LBB0_471:
	s_or_b64 exec, exec, s[6:7]
	s_cmp_lt_u32 s2, 0x80
	s_cselect_b32 s6, s36, s38
	s_cselect_b32 s7, s37, s39
	v_and_b32_e32 v250, 0x7fff, v166
	v_mov_b32_e32 v251, 0
	v_lshlrev_b64 v[250:251], 13, v[250:251]
	v_lshl_add_u64 v[250:251], s[6:7], 0, v[250:251]
	v_lshl_add_u64 v[250:251], v[250:251], 0, v[152:153]
	s_mov_b64 s[6:7], 0x20000
	global_load_dword v252, v[250:251], off
	global_load_dword v252, v[250:251], off offset:512
	v_lshl_add_u64 v[250:251], v[250:251], 0, s[6:7]
	global_load_dword v252, v[250:251], off
	global_load_dword v252, v[250:251], off offset:512
	v_lshl_add_u64 v[250:251], v[250:251], 0, s[6:7]
	global_load_dword v252, v[250:251], off
	global_load_dword v252, v[250:251], off offset:512
	v_lshl_add_u64 v[250:251], v[250:251], 0, s[6:7]
	global_load_dword v252, v[250:251], off
	global_load_dword v252, v[250:251], off offset:512
	s_mov_b64 s[6:7], 0xa0000
	v_lshl_add_u64 v[250:251], v[250:251], 0, s[6:7]
	s_mov_b64 s[6:7], 0x20000
	global_load_dword v252, v[250:251], off
	global_load_dword v252, v[250:251], off offset:512
	v_lshl_add_u64 v[250:251], v[250:251], 0, s[6:7]
	global_load_dword v252, v[250:251], off
	global_load_dword v252, v[250:251], off offset:512
	v_lshl_add_u64 v[250:251], v[250:251], 0, s[6:7]
	global_load_dword v252, v[250:251], off
	global_load_dword v252, v[250:251], off offset:512
	v_lshl_add_u64 v[250:251], v[250:251], 0, s[6:7]
	global_load_dword v252, v[250:251], off
	global_load_dword v252, v[250:251], off offset:512
	v_mul_f32_e32 v112, v109, v109
	s_waitcnt lgkmcnt(0)
	v_mul_f32_e32 v113, v111, v111
	v_fmac_f32_e32 v112, v108, v108
	v_fmac_f32_e32 v113, v110, v110
	v_add_f32_e32 v112, v112, v113
	v_mul_f32_e32 v113, v105, v105
	v_mul_f32_e32 v114, v107, v107
	v_fmac_f32_e32 v113, v104, v104
	v_fmac_f32_e32 v114, v106, v106
	v_add_f32_e32 v113, v113, v114
	v_add_f32_e32 v112, v112, v113
	v_mul_f32_e32 v113, v101, v101
	v_mul_f32_e32 v114, v103, v103
	v_fmac_f32_e32 v113, v100, v100
	v_fmac_f32_e32 v114, v102, v102
	v_add_f32_e32 v113, v113, v114
	v_mul_f32_e32 v114, v97, v97
	v_mul_f32_e32 v115, v99, v99
	v_fmac_f32_e32 v114, v96, v96
	v_fmac_f32_e32 v115, v98, v98
	v_add_f32_e32 v114, v114, v115
	v_add_f32_e32 v113, v113, v114
	v_add_f32_e32 v112, v112, v113
	ds_bpermute_b32 v113, v222, v112
	s_waitcnt lgkmcnt(0)
	v_add_f32_e32 v112, v112, v113
	ds_bpermute_b32 v113, v223, v112
	s_and_saveexec_b64 s[6:7], s[0:1]
	s_cbranch_execz .LBB0_473
	s_waitcnt lgkmcnt(0)
	v_add_f32_e32 v112, v112, v113
	global_atomic_add_f32 v[172:173], v112, off offset:64
